# v_k9 + attn_scan: only workgroups in CU slot 0 (HW_ID TG_ID) claim the 128 scan items via their own counter - never two scans on one CU, independent of block placement
# speedup vs baseline: 1.0370x; 1.0059x over previous
; DI void phase_attn_scan(const Params& p, int l, int half, char* smem, int rep) {
;   __shared__ int s_item;
;   const int n_scan = 128, n_lat = 3 * 512, n_ctx = (l == 0) ? 96 : 0;
;   const int n_gate = ((l == 0) ? 68 : 64) * 32;
;   const int n_conv = (l == 0 && half == 0) ? 128 : 0;
;   const int total = n_scan + n_conv + n_lat + n_ctx + n_gate;
;   unsigned* cnt = p.cnt + (l * 2 + half) + 8 * rep;
;   for (;;) {
;     __syncthreads();
;     if (threadIdx.x == 0) s_item = (int)atomicAdd(cnt, 1u);
;     __syncthreads();
;     int it = s_item;
;     if (it >= total) break;
.LBB0_151:
	s_and_b64 vcc, exec, s[0:1]
	s_cbranch_vccz .LBB0_941
	v_readlane_b32 s0, v255, 20
	s_cmp_gt_i32 s0, 0
	s_mov_b64 s[0:1], -1
	s_cbranch_scc0 .LBB0_939
	v_readlane_b32 s0, v255, 20
	s_cmp_gt_i32 s0, 1
	s_mov_b64 s[0:1], -1
	s_cbranch_scc0 .LBB0_408
	v_readlane_b32 s0, v252, 2
	s_add_i32 s0, s0, 11
	s_cmp_gt_u32 s0, 26
	s_cselect_b64 s[12:13], -1, 0
	v_writelane_b32 v255, s12, 25
	v_readlane_b32 s1, v252, 3
	s_mov_b64 s[86:87], s[66:67]
	v_writelane_b32 v255, s13, 26
	s_mov_b64 s[84:85], s[64:65]
	v_readlane_b32 s12, v255, 17
	v_readlane_b32 s26, v255, 19
	s_or_b32 s1, s26, s12
	s_cmp_eq_u32 s1, 0
	s_mov_b64 s[82:83], s[62:63]
	s_mov_b64 s[80:81], s[60:61]
	s_mov_b64 s[78:79], s[58:59]
	s_mov_b64 s[76:77], s[56:57]
	s_mov_b64 s[74:75], s[54:55]
	s_mov_b64 s[72:73], s[52:53]
	s_mov_b32 s60, s12
	s_cselect_b32 s12, 0x80, 0
	s_cmp_lt_u32 s0, 27
	s_movk_i32 s0, 0x880
	s_cselect_b32 s21, s0, 0x800
	s_movk_i32 s0, 0xf0a0
	s_cselect_b32 s0, s0, 0xfffff180
	v_readlane_b32 s13, v255, 18
	v_writelane_b32 v255, s0, 30
	s_movk_i32 s0, 0xf920
	s_cselect_b32 s13, 0x60, 0
	s_cselect_b32 s0, s0, 0xfffff980
	v_writelane_b32 v255, s0, 27
	s_or_b32 s0, s21, s13
	s_add_i32 s0, s0, s12
	s_add_i32 s69, s0, 0x680
	s_lshl_b32 s0, s60, 1
	s_add_i32 s0, s0, s26
	s_ashr_i32 s1, s0, 31
	s_lshl_b64 s[0:1], s[0:1], 2
	s_add_u32 s0, s74, s0
	s_addc_u32 s1, s75, s1
	v_writelane_b32 v255, s0, 23
	s_lshl_b32 s28, s12, 8
	s_ashr_i32 s61, s60, 31
	v_writelane_b32 v255, s1, 24
	s_or_b32 s0, s13, 0x600
	v_writelane_b32 v255, s0, 32
	s_or_b32 s0, s0, s21
	v_writelane_b32 v255, s0, 28
	s_mul_i32 s0, s26, 0x4400
	v_writelane_b32 v255, s0, 34
	s_ashr_i32 s0, s0, 31
	s_mul_i32 s1, s60, 0x1f00
	v_writelane_b32 v255, s0, 35
	s_mul_hi_i32 s0, s60, 0x1f00
	s_add_u32 s1, s1, 0xf00
	v_writelane_b32 v255, s1, 36
	s_addc_u32 s0, s0, 0
	v_writelane_b32 v255, s0, 37
	s_lshl_b32 s0, s60, 12
	s_ashr_i32 s1, s0, 31
	s_lshl_b32 s12, s60, 6
	v_readlane_b32 s36, v252, 38
	s_ashr_i32 s13, s12, 31
	s_lshl_b64 s[0:1], s[0:1], 2
	v_readlane_b32 s38, v252, 40
	v_readlane_b32 s39, v252, 41
	s_add_u32 s0, s38, s0
	v_writelane_b32 v255, s0, 38
	s_addc_u32 s0, s39, s1
	v_writelane_b32 v255, s0, 39
	s_mov_b32 s0, s60
	v_writelane_b32 v255, s0, 17
	v_readlane_b32 s37, v252, 39
	s_mov_b32 s29, s27
	v_writelane_b32 v255, s1, 18
	s_lshl_b64 s[0:1], s[60:61], 2
	s_mov_b64 s[52:53], s[72:73]
	s_add_u32 s0, s52, s0
	s_addc_u32 s1, s53, s1
	v_writelane_b32 v255, s0, 40
	s_mov_b64 s[54:55], s[74:75]
	s_mov_b64 s[56:57], s[76:77]
	v_writelane_b32 v255, s1, 41
	s_lshl_b64 s[0:1], s[12:13], 2
	s_add_u32 s0, s36, s0
	s_addc_u32 s1, s37, s1
	v_writelane_b32 v255, s0, 42
	s_mov_b64 s[58:59], s[78:79]
	s_mov_b64 s[60:61], s[80:81]
	s_mov_b64 s[62:63], s[82:83]
	s_mov_b64 s[64:65], s[84:85]
	s_mov_b64 s[66:67], s[86:87]
	v_writelane_b32 v255, s1, 43
	v_readlane_b32 s40, v252, 42
	v_readlane_b32 s41, v252, 43
	v_readlane_b32 s42, v252, 44
	v_readlane_b32 s43, v252, 45
	v_readlane_b32 s44, v252, 46
	v_readlane_b32 s45, v252, 47
	v_readlane_b32 s46, v252, 48
	v_readlane_b32 s47, v252, 49
	v_readlane_b32 s48, v252, 50
	v_readlane_b32 s49, v252, 51
	v_readlane_b32 s50, v252, 52
	v_readlane_b32 s51, v252, 53
	s_getreg_b32 s0, hwreg(HW_REG_HW_ID, 16, 4)
	s_cmp_eq_u32 s0, 0
	s_cselect_b32 s1, 1, 0
	s_nop 0
	v_writelane_b32 v255, s1, 59
	s_branch .LBB0_158

; DI void phase_attn_scan(const Params& p, int l, int half, char* smem, int rep) {
;     ...
;   for (;;) {
;     __syncthreads();
;     if (threadIdx.x == 0) s_item = (int)atomicAdd(cnt, 1u);
;     __syncthreads();
;     int it = s_item;
;     if (it >= total) break;
;     if (it < n_scan) { scan_item(p, it, smem); continue; }
.LBB0_158:
	s_barrier
	s_mov_b64 s[0:1], exec
	v_readlane_b32 s12, v252, 0
	v_readlane_b32 s13, v252, 1
	s_and_b64 s[12:13], s[0:1], s[12:13]
	s_mov_b64 exec, s[12:13]
	s_cbranch_execz .LBB0_162
	v_readlane_b32 s12, v255, 59
	s_cmp_eq_u32 s12, 0
	s_cbranch_scc1 .Lq_fetch
	v_writelane_b32 v255, 0, 59
	s_waitcnt vmcnt(3)
	v_readlane_b32 s36, v255, 23
	v_readlane_b32 s37, v255, 24
	v_mov_b32_e32 v1, 1
	s_nop 4
	global_atomic_add v1, v177, v1, s[36:37] offset:128 sc0
	s_waitcnt vmcnt(0)
	v_readfirstlane_b32 s12, v1
	s_cmpk_lt_u32 s12, 0x80
	s_cbranch_scc0 .Lq_fetch
	v_mov_b32_e32 v0, s12
	ds_write_b32 v200, v0
	s_branch .LBB0_162
